# allocation E1: phase-7 tail converts Mamba in/out-proj weights only (176 MB); layer-0 ffn_down back in phase 0
# speedup vs baseline: 1.0250x; 1.0018x over previous
; #define LAS __attribute__((address_space(3)))
; __device__ __forceinline__ void xpose_item(const float* src, int ld, bf16_t* dst, int K, int k0, LAS float* scr, int lane, const float* gk) {
;     if (src) {
; #pragma unroll 8
;         for (int i = 0; i < 32; ++i) { const int kk = 2 * i + (lane >> 5); scr[kk * 33 + (lane & 31)] = __builtin_nontemporal_load(src + (size_t)(k0 + kk) * ld + (lane & 31)); }
;     } else {
; #pragma unroll 8
;         for (int i = 0; i < 32; ++i) { const int kk = 2 * i + (lane >> 5); scr[kk * 33 + (lane & 31)] = 0.f; }
;     }
;     const int c = lane & 7;
;     f32x4 g0 = (f32x4){1.f, 1.f, 1.f, 1.f}, g1 = g0;
;     if (gk) { g0 = *(const f32x4*)(gk + k0 + 8 * c); g1 = *(const f32x4*)(gk + k0 + 8 * c + 4); }
; __global__ void __launch_bounds__(512) mega(Args a_byval) {
;     ...
;                 it = xpose_all(a.in[22], nullptr, 2048, 4096, 2048, 2048, 0, (bf16_t*)(ws + WS_WB_OUT), it, NGW, scr, lane);
.LBB0_418:
	s_waitcnt vmcnt(0)
	s_barrier
	s_cmp_lg_u32 s76, 7
	s_cbranch_scc1 .Lxt7_done
	v_readlane_b32 s59, v255, 5
	s_cmpk_lg_i32 s59, 0x100
	s_cbranch_scc1 .Lxt7_done
	s_cmpk_lt_i32 s94, 0x80
	s_cbranch_scc1 .Lxt7_done
	s_sub_i32 s59, s94, 0x80
	s_lshl_b32 s59, s59, 3
	s_add_i32 s59, s59, s95
	s_mul_i32 s64, s95, 0x2100
	v_and_b32_e32 v2, 31, v200
	v_lshrrev_b32_e32 v3, 5, v200
	v_lshlrev_b32_e32 v4, 2, v2
	v_mul_u32_u24_e32 v6, 0x84, v3
	v_add3_u32 v6, v6, v4, s64
	v_and_b32_e32 v7, 7, v200
	v_lshrrev_b32_e32 v8, 3, v200
	v_mul_u32_u24_e32 v9, 0x420, v7
	v_lshl_add_u32 v9, v8, 2, v9
	v_add_u32_e32 v9, s64, v9
	s_cmpk_ge_i32 s59, 0x1000
	s_cbranch_scc1 .Lxpwo_end
	s_load_dwordx2 s[60:61], s[92:93], 0xb0
	s_load_dwordx2 s[62:63], s[92:93], 0xe8
	v_mov_b32_e32 v5, 0x2000
	v_mul_u32_u24_e32 v5, v3, v5
	v_add_u32_e32 v5, v5, v4
	v_mov_b32_e32 v10, 0x2000
	v_mul_u32_u24_e32 v10, v8, v10
	v_lshl_add_u32 v12, v7, 4, v10
	v_add_u32_e32 v13, 0x10000, v12
	v_add_u32_e32 v14, 0x20000, v12
	v_add_u32_e32 v15, 0x30000, v12
	s_waitcnt lgkmcnt(0)
	s_add_u32 s62, s62, 0xad00000
	s_addc_u32 s63, s63, 0
	s_lshr_b32 s64, s59, 6
	s_and_b32 s65, s59, 63
	s_mul_i32 s66, s64, 0x80000
	s_lshl_b32 s67, s65, 7
	s_add_i32 s66, s66, s67
	s_add_u32 s66, s60, s66
	s_addc_u32 s67, s61, 0
	v_mov_b32_e32 v11, v5
	global_load_dword v20, v11, s[66:67] nt
	v_add_u32_e32 v11, 0x4000, v11
	global_load_dword v21, v11, s[66:67] nt
	v_add_u32_e32 v11, 0x4000, v11
	global_load_dword v22, v11, s[66:67] nt
	v_add_u32_e32 v11, 0x4000, v11
	global_load_dword v23, v11, s[66:67] nt
	v_add_u32_e32 v11, 0x4000, v11
	global_load_dword v24, v11, s[66:67] nt
	v_add_u32_e32 v11, 0x4000, v11
	global_load_dword v25, v11, s[66:67] nt
	v_add_u32_e32 v11, 0x4000, v11
	global_load_dword v26, v11, s[66:67] nt
	v_add_u32_e32 v11, 0x4000, v11
	global_load_dword v27, v11, s[66:67] nt
	v_add_u32_e32 v11, 0x4000, v11
	global_load_dword v28, v11, s[66:67] nt
	v_add_u32_e32 v11, 0x4000, v11
	global_load_dword v29, v11, s[66:67] nt
	v_add_u32_e32 v11, 0x4000, v11
	global_load_dword v30, v11, s[66:67] nt
	v_add_u32_e32 v11, 0x4000, v11
	global_load_dword v31, v11, s[66:67] nt
	v_add_u32_e32 v11, 0x4000, v11
	global_load_dword v32, v11, s[66:67] nt
	v_add_u32_e32 v11, 0x4000, v11
	global_load_dword v33, v11, s[66:67] nt
	v_add_u32_e32 v11, 0x4000, v11
	global_load_dword v34, v11, s[66:67] nt
	v_add_u32_e32 v11, 0x4000, v11
	global_load_dword v35, v11, s[66:67] nt
	v_add_u32_e32 v11, 0x4000, v11
	global_load_dword v36, v11, s[66:67] nt
	v_add_u32_e32 v11, 0x4000, v11
	global_load_dword v37, v11, s[66:67] nt
	v_add_u32_e32 v11, 0x4000, v11
	global_load_dword v38, v11, s[66:67] nt
	v_add_u32_e32 v11, 0x4000, v11
	global_load_dword v39, v11, s[66:67] nt
	v_add_u32_e32 v11, 0x4000, v11
	global_load_dword v40, v11, s[66:67] nt
	v_add_u32_e32 v11, 0x4000, v11
	global_load_dword v41, v11, s[66:67] nt
	v_add_u32_e32 v11, 0x4000, v11
	global_load_dword v42, v11, s[66:67] nt
	v_add_u32_e32 v11, 0x4000, v11
	global_load_dword v43, v11, s[66:67] nt
	v_add_u32_e32 v11, 0x4000, v11
	global_load_dword v44, v11, s[66:67] nt
	v_add_u32_e32 v11, 0x4000, v11
	global_load_dword v45, v11, s[66:67] nt
	v_add_u32_e32 v11, 0x4000, v11
	global_load_dword v46, v11, s[66:67] nt
	v_add_u32_e32 v11, 0x4000, v11
	global_load_dword v47, v11, s[66:67] nt
	v_add_u32_e32 v11, 0x4000, v11
	global_load_dword v48, v11, s[66:67] nt
	v_add_u32_e32 v11, 0x4000, v11
	global_load_dword v49, v11, s[66:67] nt
	v_add_u32_e32 v11, 0x4000, v11
	global_load_dword v50, v11, s[66:67] nt
	v_add_u32_e32 v11, 0x4000, v11
	global_load_dword v51, v11, s[66:67] nt
